# pair-wise K-slice issue spread over three slots per odd step for all waves (2/2/4 loads) instead of per-wave-group bursts
# baseline (speedup 1.0000x reference)
.LBB0_112:
	v_readfirstlane_b32 s16, v163
	v_readfirstlane_b32 s12, v166
	v_mov_b32_e32 v128, 0
	v_mov_b32_e32 v129, 0
	v_mov_b32_e32 v130, 0
	v_mov_b32_e32 v131, 0
	v_mov_b32_e32 v132, 0
	v_mov_b32_e32 v133, 0
	v_mov_b32_e32 v134, 0
	v_mov_b32_e32 v135, 0
	v_mov_b32_e32 v136, 0
	v_mov_b32_e32 v137, 0
	v_mov_b32_e32 v138, 0
	v_mov_b32_e32 v139, 0
	v_mov_b32_e32 v140, 0
	v_mov_b32_e32 v141, 0
	v_mov_b32_e32 v142, 0
	v_mov_b32_e32 v143, 0
	v_mov_b32_e32 v168, 0
	v_mov_b32_e32 v169, 0
	v_mov_b32_e32 v170, 0
	v_mov_b32_e32 v171, 0
	v_mov_b32_e32 v172, 0
	v_mov_b32_e32 v173, 0
	v_mov_b32_e32 v174, 0
	v_mov_b32_e32 v175, 0
	s_lshr_b32 s12, s12, 8
	s_cmp_eq_u32 s12, 0
	s_mov_b32 s17, 28
	s_mov_b32 s11, 0
	s_lshl_b32 s10, s36, 15
	v_or_b32_e32 v254, s10, v165
	v_add_u32_e32 v254, v254, v162
	v_add_u32_e32 v152, s10, v164
	v_add_u32_e32 v152, v152, v162
	s_waitcnt vmcnt(12)

.Lg0_Ew:
.Lg0_O:
	s_waitcnt lgkmcnt(0)
	s_barrier
	ds_read_b128 v[128:131], v254 offset:16384
	ds_read_b128 v[132:135], v254 offset:17408
	ds_read_b128 v[148:151], v152
	ds_read_b128 v[144:147], v152 offset:1024
	v_mfma_f32_16x16x32_bf16 v[24:27], v[246:249], v[168:171], v[24:27]
	v_mfma_f32_16x16x32_bf16 v[20:23], v[250:253], v[168:171], v[20:23]
	v_mfma_f32_16x16x32_bf16 v[16:19], v[136:139], v[168:171], v[16:19]
	v_mfma_f32_16x16x32_bf16 v[12:15], v[140:143], v[168:171], v[12:15]
	v_mfma_f32_16x16x32_bf16 v[8:11], v[246:249], v[172:175], v[8:11]
	v_mfma_f32_16x16x32_bf16 v[4:7], v[250:253], v[172:175], v[4:7]
	v_mfma_f32_16x16x32_bf16 v[0:3], v[136:139], v[172:175], v[0:3]
	v_mfma_f32_16x16x32_bf16 v[36:39], v[140:143], v[172:175], v[36:39]
	ds_read_b128 v[136:139], v254 offset:18432
	ds_read_b128 v[140:143], v254 offset:19456
	s_cmp_lt_u32 s35, s17
	s_cbranch_scc0 .Lg0_O_sa
	s_sub_u32 s8, s8, 64
	s_subb_u32 s9, s9, 0
	s_cmp_gt_i32 s36, 0
	s_cselect_b32 s12, -1, 4
	s_add_i32 s12, s12, s36
	s_lshl_b32 s12, s12, 15
	s_add_i32 s12, s12, s16
	s_cmp_gt_i32 s36, 1
	s_cselect_b32 s10, -2, 3
	s_add_i32 s10, s10, s36
	s_lshl_b32 s10, s10, 15
	s_add_i32 s10, s10, s16
	s_mov_b32 m0, s10
	v_lshl_add_u64 v[168:169], v[160:161], 0, s[8:9]
	global_load_lds_dwordx4 v[168:169], off
	s_mov_b32 m0, s12
	v_lshl_add_u64 v[168:169], v[168:169], 0, 64
	global_load_lds_dwordx4 v[168:169], off
	s_add_u32 s8, s8, 64
	s_addc_u32 s9, s9, 0
.Lg0_O_sa:
	ds_read_b128 v[168:171], v152 offset:2048
	ds_read_b128 v[172:175], v152 offset:3072
	s_waitcnt lgkmcnt(4)
	v_mfma_f32_16x16x32_bf16 v[124:127], v[128:131], v[148:151], v[124:127]
	v_mfma_f32_16x16x32_bf16 v[120:123], v[132:135], v[148:151], v[120:123]
	v_mfma_f32_16x16x32_bf16 v[108:111], v[128:131], v[144:147], v[108:111]
	v_mfma_f32_16x16x32_bf16 v[104:107], v[132:135], v[144:147], v[104:107]
	s_waitcnt lgkmcnt(2)
	v_mfma_f32_16x16x32_bf16 v[116:119], v[136:139], v[148:151], v[116:119]
	v_mfma_f32_16x16x32_bf16 v[112:115], v[140:143], v[148:151], v[112:115]
	v_mfma_f32_16x16x32_bf16 v[100:103], v[136:139], v[144:147], v[100:103]
	v_mfma_f32_16x16x32_bf16 v[96:99], v[140:143], v[144:147], v[96:99]
	s_cmp_lt_u32 s35, s17
	s_cbranch_scc0 .Lg0_O_sb1
	s_sub_u32 s8, s8, 64
	s_subb_u32 s9, s9, 0
	s_cmp_gt_i32 s36, 0
	s_cselect_b32 s12, -1, 4
	s_add_i32 s12, s12, s36
	s_lshl_b32 s12, s12, 15
	s_add_i32 s12, s12, s16
	s_cmp_gt_i32 s36, 1
	s_cselect_b32 s10, -2, 3
	s_add_i32 s10, s10, s36
	s_lshl_b32 s10, s10, 15
	s_add_i32 s10, s10, s16
	s_add_u32 m0, s10, 0x2000
	v_lshl_add_u64 v[148:149], v[158:159], 0, s[8:9]
	global_load_lds_dwordx4 v[148:149], off
	s_add_u32 m0, s12, 0x2000
	v_lshl_add_u64 v[148:149], v[148:149], 0, 64
	global_load_lds_dwordx4 v[148:149], off
	s_add_u32 s8, s8, 64
	s_addc_u32 s9, s9, 0
.Lg0_O_sb1:
	s_waitcnt lgkmcnt(0)
	v_mfma_f32_16x16x32_bf16 v[92:95], v[128:131], v[168:171], v[92:95]
	ds_read_b128 v[144:147], v152 offset:4096
	ds_read_b128 v[148:151], v152 offset:5120
	v_mfma_f32_16x16x32_bf16 v[88:91], v[132:135], v[168:171], v[88:91]
	v_mfma_f32_16x16x32_bf16 v[84:87], v[136:139], v[168:171], v[84:87]
	v_mfma_f32_16x16x32_bf16 v[80:83], v[140:143], v[168:171], v[80:83]
	v_mfma_f32_16x16x32_bf16 v[76:79], v[128:131], v[172:175], v[76:79]
	v_mfma_f32_16x16x32_bf16 v[72:75], v[132:135], v[172:175], v[72:75]
	v_mfma_f32_16x16x32_bf16 v[68:71], v[136:139], v[172:175], v[68:71]
	v_mfma_f32_16x16x32_bf16 v[64:67], v[140:143], v[172:175], v[64:67]
	s_cmp_lt_u32 s35, s17
	s_cbranch_scc0 .Lg0_O_sb
	s_sub_u32 s8, s8, 64
	s_subb_u32 s9, s9, 0
	s_cmp_gt_i32 s36, 0
	s_cselect_b32 s12, -1, 4
	s_add_i32 s12, s12, s36
	s_lshl_b32 s12, s12, 15
	s_add_i32 s12, s12, s16
	s_cmp_gt_i32 s36, 1
	s_cselect_b32 s10, -2, 3
	s_add_i32 s10, s10, s36
	s_lshl_b32 s10, s10, 15
	s_add_i32 s10, s10, s16
	s_add_u32 m0, s10, 0x4000
	v_lshl_add_u64 v[168:169], v[156:157], 0, s[8:9]
	global_load_lds_dwordx4 v[168:169], off
	s_add_u32 m0, s12, 0x4000
	v_lshl_add_u64 v[168:169], v[168:169], 0, 64
	global_load_lds_dwordx4 v[168:169], off
	s_add_u32 m0, s10, 0x6000
	v_lshl_add_u64 v[168:169], v[154:155], 0, s[8:9]
	global_load_lds_dwordx4 v[168:169], off
	s_add_u32 m0, s12, 0x6000
	v_lshl_add_u64 v[168:169], v[168:169], 0, 64
	global_load_lds_dwordx4 v[168:169], off
	s_add_u32 s8, s8, 64
	s_addc_u32 s9, s9, 0

.LBB0_244:
	v_readfirstlane_b32 s36, v199
	v_readfirstlane_b32 s30, v166
	v_mov_b32_e32 v130, 0
	v_mov_b32_e32 v131, 0
	v_mov_b32_e32 v132, 0
	v_mov_b32_e32 v133, 0
	v_mov_b32_e32 v134, 0
	v_mov_b32_e32 v135, 0
	v_mov_b32_e32 v136, 0
	v_mov_b32_e32 v137, 0
	v_mov_b32_e32 v138, 0
	v_mov_b32_e32 v139, 0
	v_mov_b32_e32 v140, 0
	v_mov_b32_e32 v141, 0
	v_mov_b32_e32 v142, 0
	v_mov_b32_e32 v143, 0
	v_mov_b32_e32 v144, 0
	v_mov_b32_e32 v145, 0
	v_mov_b32_e32 v200, 0
	v_mov_b32_e32 v201, 0
	v_mov_b32_e32 v202, 0
	v_mov_b32_e32 v203, 0
	v_mov_b32_e32 v204, 0
	v_mov_b32_e32 v205, 0
	v_mov_b32_e32 v206, 0
	v_mov_b32_e32 v207, 0
	s_lshr_b32 s30, s30, 8
	s_cmp_eq_u32 s30, 0
	s_mov_b32 s37, 28
	s_mov_b32 s27, 0
	s_lshl_b32 s26, s60, 15
	v_or_b32_e32 v254, s26, v198
	v_add_u32_e32 v254, v254, v196
	v_add_u32_e32 v64, s26, v197
	v_add_u32_e32 v64, v64, v196
	s_waitcnt vmcnt(12)

.Lg1_Ew:
.Lg1_O:
	s_waitcnt lgkmcnt(0)
	s_barrier
	ds_read_b128 v[130:133], v254 offset:16384
	ds_read_b128 v[134:137], v254 offset:17408
	ds_read_b128 v[150:153], v64
	ds_read_b128 v[146:149], v64 offset:1024
	v_mfma_f32_16x16x32_bf16 v[28:31], v[246:249], v[200:203], v[28:31]
	v_mfma_f32_16x16x32_bf16 v[24:27], v[250:253], v[200:203], v[24:27]
	v_mfma_f32_16x16x32_bf16 v[20:23], v[138:141], v[200:203], v[20:23]
	v_mfma_f32_16x16x32_bf16 v[16:19], v[142:145], v[200:203], v[16:19]
	v_mfma_f32_16x16x32_bf16 v[12:15], v[246:249], v[204:207], v[12:15]
	v_mfma_f32_16x16x32_bf16 v[8:11], v[250:253], v[204:207], v[8:11]
	v_mfma_f32_16x16x32_bf16 v[4:7], v[138:141], v[204:207], v[4:7]
	v_mfma_f32_16x16x32_bf16 v[0:3], v[142:145], v[204:207], v[0:3]
	ds_read_b128 v[138:141], v254 offset:18432
	ds_read_b128 v[142:145], v254 offset:19456
	s_cmp_lt_u32 s25, s37
	s_cbranch_scc0 .Lg1_O_sa
	s_sub_u32 s0, s0, 64
	s_subb_u32 s1, s1, 0
	s_cmp_gt_i32 s60, 0
	s_cselect_b32 s30, -1, 4
	s_add_i32 s30, s30, s60
	s_lshl_b32 s30, s30, 15
	s_add_i32 s30, s30, s36
	s_cmp_gt_i32 s60, 1
	s_cselect_b32 s26, -2, 3
	s_add_i32 s26, s26, s60
	s_lshl_b32 s26, s26, 15
	s_add_i32 s26, s26, s36
	s_mov_b32 m0, s26
	v_lshl_add_u64 v[200:201], v[164:165], 0, s[0:1]
	global_load_lds_dwordx4 v[200:201], off
	s_mov_b32 m0, s30
	v_lshl_add_u64 v[200:201], v[200:201], 0, 64
	global_load_lds_dwordx4 v[200:201], off
	s_add_u32 s0, s0, 64
	s_addc_u32 s1, s1, 0
.Lg1_O_sa:
	ds_read_b128 v[200:203], v64 offset:2048
	ds_read_b128 v[204:207], v64 offset:3072
	s_waitcnt lgkmcnt(4)
	v_mfma_f32_16x16x32_bf16 v[126:129], v[130:133], v[150:153], v[126:129]
	v_mfma_f32_16x16x32_bf16 v[122:125], v[134:137], v[150:153], v[122:125]
	v_mfma_f32_16x16x32_bf16 v[110:113], v[130:133], v[146:149], v[110:113]
	v_mfma_f32_16x16x32_bf16 v[106:109], v[134:137], v[146:149], v[106:109]
	s_waitcnt lgkmcnt(2)
	v_mfma_f32_16x16x32_bf16 v[118:121], v[138:141], v[150:153], v[118:121]
	v_mfma_f32_16x16x32_bf16 v[114:117], v[142:145], v[150:153], v[114:117]
	v_mfma_f32_16x16x32_bf16 v[102:105], v[138:141], v[146:149], v[102:105]
	v_mfma_f32_16x16x32_bf16 v[98:101], v[142:145], v[146:149], v[98:101]
	s_cmp_lt_u32 s25, s37
	s_cbranch_scc0 .Lg1_O_sb1
	s_sub_u32 s0, s0, 64
	s_subb_u32 s1, s1, 0
	s_cmp_gt_i32 s60, 0
	s_cselect_b32 s30, -1, 4
	s_add_i32 s30, s30, s60
	s_lshl_b32 s30, s30, 15
	s_add_i32 s30, s30, s36
	s_cmp_gt_i32 s60, 1
	s_cselect_b32 s26, -2, 3
	s_add_i32 s26, s26, s60
	s_lshl_b32 s26, s26, 15
	s_add_i32 s26, s26, s36
	s_add_u32 m0, s26, 0x2000
	v_lshl_add_u64 v[150:151], v[162:163], 0, s[0:1]
	global_load_lds_dwordx4 v[150:151], off
	s_add_u32 m0, s30, 0x2000
	v_lshl_add_u64 v[150:151], v[150:151], 0, 64
	global_load_lds_dwordx4 v[150:151], off
	s_add_u32 s0, s0, 64
	s_addc_u32 s1, s1, 0
.Lg1_O_sb1:
	s_waitcnt lgkmcnt(0)
	v_mfma_f32_16x16x32_bf16 v[94:97], v[130:133], v[200:203], v[94:97]
	ds_read_b128 v[146:149], v64 offset:4096
	ds_read_b128 v[150:153], v64 offset:5120
	v_mfma_f32_16x16x32_bf16 v[90:93], v[134:137], v[200:203], v[90:93]
	v_mfma_f32_16x16x32_bf16 v[86:89], v[138:141], v[200:203], v[86:89]
	v_mfma_f32_16x16x32_bf16 v[82:85], v[142:145], v[200:203], v[82:85]
	v_mfma_f32_16x16x32_bf16 v[78:81], v[130:133], v[204:207], v[78:81]
	v_mfma_f32_16x16x32_bf16 v[74:77], v[134:137], v[204:207], v[74:77]
	v_mfma_f32_16x16x32_bf16 v[70:73], v[138:141], v[204:207], v[70:73]
	v_mfma_f32_16x16x32_bf16 v[66:69], v[142:145], v[204:207], v[66:69]
	s_cmp_lt_u32 s25, s37
	s_cbranch_scc0 .Lg1_O_sb
	s_sub_u32 s0, s0, 64
	s_subb_u32 s1, s1, 0
	s_cmp_gt_i32 s60, 0
	s_cselect_b32 s30, -1, 4
	s_add_i32 s30, s30, s60
	s_lshl_b32 s30, s30, 15
	s_add_i32 s30, s30, s36
	s_cmp_gt_i32 s60, 1
	s_cselect_b32 s26, -2, 3
	s_add_i32 s26, s26, s60
	s_lshl_b32 s26, s26, 15
	s_add_i32 s26, s26, s36
	s_add_u32 m0, s26, 0x4000
	v_lshl_add_u64 v[200:201], v[160:161], 0, s[0:1]
	global_load_lds_dwordx4 v[200:201], off
	s_add_u32 m0, s30, 0x4000
	v_lshl_add_u64 v[200:201], v[200:201], 0, 64
	global_load_lds_dwordx4 v[200:201], off
	s_add_u32 m0, s26, 0x6000
	v_lshl_add_u64 v[200:201], v[158:159], 0, s[0:1]
	global_load_lds_dwordx4 v[200:201], off
	s_add_u32 m0, s30, 0x6000
	v_lshl_add_u64 v[200:201], v[200:201], 0, 64
	global_load_lds_dwordx4 v[200:201], off
	s_add_u32 s0, s0, 64
	s_addc_u32 s1, s1, 0

.LBB0_617:
	v_readfirstlane_b32 s36, v200
	v_readfirstlane_b32 s28, v166
	v_mov_b32_e32 v130, 0
	v_mov_b32_e32 v131, 0
	v_mov_b32_e32 v132, 0
	v_mov_b32_e32 v133, 0
	v_mov_b32_e32 v134, 0
	v_mov_b32_e32 v135, 0
	v_mov_b32_e32 v136, 0
	v_mov_b32_e32 v137, 0
	v_mov_b32_e32 v138, 0
	v_mov_b32_e32 v139, 0
	v_mov_b32_e32 v140, 0
	v_mov_b32_e32 v141, 0
	v_mov_b32_e32 v142, 0
	v_mov_b32_e32 v143, 0
	v_mov_b32_e32 v144, 0
	v_mov_b32_e32 v145, 0
	v_mov_b32_e32 v202, 0
	v_mov_b32_e32 v203, 0
	v_mov_b32_e32 v204, 0
	v_mov_b32_e32 v205, 0
	v_mov_b32_e32 v206, 0
	v_mov_b32_e32 v207, 0
	v_mov_b32_e32 v208, 0
	v_mov_b32_e32 v209, 0
	s_lshr_b32 s28, s28, 8
	s_cmp_eq_u32 s28, 0
	s_mov_b32 s37, 28
	s_mov_b32 s27, 0
	s_lshl_b32 s26, s79, 15
	v_or_b32_e32 v254, s26, v199
	v_add_u32_e32 v254, v254, v197
	v_add_u32_e32 v64, s26, v198
	v_add_u32_e32 v64, v64, v197
	s_waitcnt vmcnt(12)

.Lg2_Ew:
.Lg2_O:
	s_waitcnt lgkmcnt(0)
	s_barrier
	ds_read_b128 v[130:133], v254 offset:16384
	ds_read_b128 v[134:137], v254 offset:17408
	ds_read_b128 v[150:153], v64
	ds_read_b128 v[146:149], v64 offset:1024
	v_mfma_f32_16x16x32_bf16 v[102:105], v[246:249], v[202:205], v[102:105]
	v_mfma_f32_16x16x32_bf16 v[70:73], v[250:253], v[202:205], v[70:73]
	v_mfma_f32_16x16x32_bf16 v[36:39], v[138:141], v[202:205], v[36:39]
	v_mfma_f32_16x16x32_bf16 v[4:7], v[142:145], v[202:205], v[4:7]
	v_mfma_f32_16x16x32_bf16 v[98:101], v[246:249], v[206:209], v[98:101]
	v_mfma_f32_16x16x32_bf16 v[66:69], v[250:253], v[206:209], v[66:69]
	v_mfma_f32_16x16x32_bf16 v[28:31], v[138:141], v[206:209], v[28:31]
	v_mfma_f32_16x16x32_bf16 v[0:3], v[142:145], v[206:209], v[0:3]
	ds_read_b128 v[138:141], v254 offset:18432
	ds_read_b128 v[142:145], v254 offset:19456
	s_cmp_lt_u32 s25, s37
	s_cbranch_scc0 .Lg2_O_sa
	s_sub_u32 s0, s0, 64
	s_subb_u32 s1, s1, 0
	s_cmp_gt_i32 s79, 0
	s_cselect_b32 s28, -1, 4
	s_add_i32 s28, s28, s79
	s_lshl_b32 s28, s28, 15
	s_add_i32 s28, s28, s36
	s_cmp_gt_i32 s79, 1
	s_cselect_b32 s26, -2, 3
	s_add_i32 s26, s26, s79
	s_lshl_b32 s26, s26, 15
	s_add_i32 s26, s26, s36
	s_mov_b32 m0, s26
	v_lshl_add_u64 v[202:203], v[164:165], 0, s[0:1]
	global_load_lds_dwordx4 v[202:203], off
	s_mov_b32 m0, s28
	v_lshl_add_u64 v[202:203], v[202:203], 0, 64
	global_load_lds_dwordx4 v[202:203], off
	s_add_u32 s0, s0, 64
	s_addc_u32 s1, s1, 0
.Lg2_O_sa:
	ds_read_b128 v[202:205], v64 offset:2048
	ds_read_b128 v[206:209], v64 offset:3072
	s_waitcnt lgkmcnt(4)
	v_mfma_f32_16x16x32_bf16 v[126:129], v[130:133], v[150:153], v[126:129]
	v_mfma_f32_16x16x32_bf16 v[94:97], v[134:137], v[150:153], v[94:97]
	v_mfma_f32_16x16x32_bf16 v[122:125], v[130:133], v[146:149], v[122:125]
	v_mfma_f32_16x16x32_bf16 v[90:93], v[134:137], v[146:149], v[90:93]
	s_waitcnt lgkmcnt(2)
	v_mfma_f32_16x16x32_bf16 v[60:63], v[138:141], v[150:153], v[60:63]
	v_mfma_f32_16x16x32_bf16 v[32:35], v[142:145], v[150:153], v[32:35]
	v_mfma_f32_16x16x32_bf16 v[56:59], v[138:141], v[146:149], v[56:59]
	v_mfma_f32_16x16x32_bf16 v[24:27], v[142:145], v[146:149], v[24:27]
	s_cmp_lt_u32 s25, s37
	s_cbranch_scc0 .Lg2_O_sb1
	s_sub_u32 s0, s0, 64
	s_subb_u32 s1, s1, 0
	s_cmp_gt_i32 s79, 0
	s_cselect_b32 s28, -1, 4
	s_add_i32 s28, s28, s79
	s_lshl_b32 s28, s28, 15
	s_add_i32 s28, s28, s36
	s_cmp_gt_i32 s79, 1
	s_cselect_b32 s26, -2, 3
	s_add_i32 s26, s26, s79
	s_lshl_b32 s26, s26, 15
	s_add_i32 s26, s26, s36
	s_add_u32 m0, s26, 0x2000
	v_lshl_add_u64 v[150:151], v[162:163], 0, s[0:1]
	global_load_lds_dwordx4 v[150:151], off
	s_add_u32 m0, s28, 0x2000
	v_lshl_add_u64 v[150:151], v[150:151], 0, 64
	global_load_lds_dwordx4 v[150:151], off
	s_add_u32 s0, s0, 64
	s_addc_u32 s1, s1, 0
.Lg2_O_sb1:
	s_waitcnt lgkmcnt(0)
	v_mfma_f32_16x16x32_bf16 v[118:121], v[130:133], v[202:205], v[118:121]
	ds_read_b128 v[146:149], v64 offset:4096
	ds_read_b128 v[150:153], v64 offset:5120
	v_mfma_f32_16x16x32_bf16 v[86:89], v[134:137], v[202:205], v[86:89]
	v_mfma_f32_16x16x32_bf16 v[52:55], v[138:141], v[202:205], v[52:55]
	v_mfma_f32_16x16x32_bf16 v[20:23], v[142:145], v[202:205], v[20:23]
	v_mfma_f32_16x16x32_bf16 v[114:117], v[130:133], v[206:209], v[114:117]
	v_mfma_f32_16x16x32_bf16 v[82:85], v[134:137], v[206:209], v[82:85]
	v_mfma_f32_16x16x32_bf16 v[48:51], v[138:141], v[206:209], v[48:51]
	v_mfma_f32_16x16x32_bf16 v[16:19], v[142:145], v[206:209], v[16:19]
	s_cmp_lt_u32 s25, s37
	s_cbranch_scc0 .Lg2_O_sb
	s_sub_u32 s0, s0, 64
	s_subb_u32 s1, s1, 0
	s_cmp_gt_i32 s79, 0
	s_cselect_b32 s28, -1, 4
	s_add_i32 s28, s28, s79
	s_lshl_b32 s28, s28, 15
	s_add_i32 s28, s28, s36
	s_cmp_gt_i32 s79, 1
	s_cselect_b32 s26, -2, 3
	s_add_i32 s26, s26, s79
	s_lshl_b32 s26, s26, 15
	s_add_i32 s26, s26, s36
	s_add_u32 m0, s26, 0x4000
	v_lshl_add_u64 v[202:203], v[160:161], 0, s[0:1]
	global_load_lds_dwordx4 v[202:203], off
	s_add_u32 m0, s28, 0x4000
	v_lshl_add_u64 v[202:203], v[202:203], 0, 64
	global_load_lds_dwordx4 v[202:203], off
	s_add_u32 m0, s26, 0x6000
	v_lshl_add_u64 v[202:203], v[158:159], 0, s[0:1]
	global_load_lds_dwordx4 v[202:203], off
	s_add_u32 m0, s28, 0x6000
	v_lshl_add_u64 v[202:203], v[202:203], 0, 64
	global_load_lds_dwordx4 v[202:203], off
	s_add_u32 s0, s0, 64
	s_addc_u32 s1, s1, 0

.LBB0_1270:
	v_readfirstlane_b32 s44, v200
	v_readfirstlane_b32 s30, v166
	v_mov_b32_e32 v130, 0
	v_mov_b32_e32 v131, 0
	v_mov_b32_e32 v132, 0
	v_mov_b32_e32 v133, 0
	v_mov_b32_e32 v134, 0
	v_mov_b32_e32 v135, 0
	v_mov_b32_e32 v136, 0
	v_mov_b32_e32 v137, 0
	v_mov_b32_e32 v138, 0
	v_mov_b32_e32 v139, 0
	v_mov_b32_e32 v140, 0
	v_mov_b32_e32 v141, 0
	v_mov_b32_e32 v142, 0
	v_mov_b32_e32 v143, 0
	v_mov_b32_e32 v144, 0
	v_mov_b32_e32 v145, 0
	v_mov_b32_e32 v202, 0
	v_mov_b32_e32 v203, 0
	v_mov_b32_e32 v204, 0
	v_mov_b32_e32 v205, 0
	v_mov_b32_e32 v206, 0
	v_mov_b32_e32 v207, 0
	v_mov_b32_e32 v208, 0
	v_mov_b32_e32 v209, 0
	s_lshr_b32 s30, s30, 8
	s_cmp_eq_u32 s30, 0
	s_mov_b32 s45, 28
	s_mov_b32 s27, 0
	s_lshl_b32 s26, s75, 15
	v_or_b32_e32 v254, s26, v199
	v_add_u32_e32 v254, v254, v197
	v_add_u32_e32 v64, s26, v198
	v_add_u32_e32 v64, v64, v197
	s_waitcnt vmcnt(12)

.Lg3_Ew:
.Lg3_O:
	s_waitcnt lgkmcnt(0)
	s_barrier
	ds_read_b128 v[130:133], v254 offset:16384
	ds_read_b128 v[134:137], v254 offset:17408
	ds_read_b128 v[150:153], v64
	ds_read_b128 v[146:149], v64 offset:1024
	v_mfma_f32_16x16x32_bf16 v[28:31], v[246:249], v[202:205], v[28:31]
	v_mfma_f32_16x16x32_bf16 v[24:27], v[250:253], v[202:205], v[24:27]
	v_mfma_f32_16x16x32_bf16 v[20:23], v[138:141], v[202:205], v[20:23]
	v_mfma_f32_16x16x32_bf16 v[16:19], v[142:145], v[202:205], v[16:19]
	v_mfma_f32_16x16x32_bf16 v[12:15], v[246:249], v[206:209], v[12:15]
	v_mfma_f32_16x16x32_bf16 v[8:11], v[250:253], v[206:209], v[8:11]
	v_mfma_f32_16x16x32_bf16 v[4:7], v[138:141], v[206:209], v[4:7]
	v_mfma_f32_16x16x32_bf16 v[0:3], v[142:145], v[206:209], v[0:3]
	ds_read_b128 v[138:141], v254 offset:18432
	ds_read_b128 v[142:145], v254 offset:19456
	s_cmp_lt_u32 s25, s45
	s_cbranch_scc0 .Lg3_O_sa
	s_sub_u32 s28, s28, 64
	s_subb_u32 s29, s29, 0
	s_cmp_gt_i32 s75, 0
	s_cselect_b32 s30, -1, 4
	s_add_i32 s30, s30, s75
	s_lshl_b32 s30, s30, 15
	s_add_i32 s30, s30, s44
	s_cmp_gt_i32 s75, 1
	s_cselect_b32 s26, -2, 3
	s_add_i32 s26, s26, s75
	s_lshl_b32 s26, s26, 15
	s_add_i32 s26, s26, s44
	s_mov_b32 m0, s26
	v_lshl_add_u64 v[202:203], v[164:165], 0, s[28:29]
	global_load_lds_dwordx4 v[202:203], off
	s_mov_b32 m0, s30
	v_lshl_add_u64 v[202:203], v[202:203], 0, 64
	global_load_lds_dwordx4 v[202:203], off
	s_add_u32 s28, s28, 64
	s_addc_u32 s29, s29, 0
.Lg3_O_sa:
	ds_read_b128 v[202:205], v64 offset:2048
	ds_read_b128 v[206:209], v64 offset:3072
	s_waitcnt lgkmcnt(4)
	v_mfma_f32_16x16x32_bf16 v[126:129], v[130:133], v[150:153], v[126:129]
	v_mfma_f32_16x16x32_bf16 v[122:125], v[134:137], v[150:153], v[122:125]
	v_mfma_f32_16x16x32_bf16 v[110:113], v[130:133], v[146:149], v[110:113]
	v_mfma_f32_16x16x32_bf16 v[106:109], v[134:137], v[146:149], v[106:109]
	s_waitcnt lgkmcnt(2)
	v_mfma_f32_16x16x32_bf16 v[118:121], v[138:141], v[150:153], v[118:121]
	v_mfma_f32_16x16x32_bf16 v[114:117], v[142:145], v[150:153], v[114:117]
	v_mfma_f32_16x16x32_bf16 v[102:105], v[138:141], v[146:149], v[102:105]
	v_mfma_f32_16x16x32_bf16 v[98:101], v[142:145], v[146:149], v[98:101]
	s_cmp_lt_u32 s25, s45
	s_cbranch_scc0 .Lg3_O_sb1
	s_sub_u32 s28, s28, 64
	s_subb_u32 s29, s29, 0
	s_cmp_gt_i32 s75, 0
	s_cselect_b32 s30, -1, 4
	s_add_i32 s30, s30, s75
	s_lshl_b32 s30, s30, 15
	s_add_i32 s30, s30, s44
	s_cmp_gt_i32 s75, 1
	s_cselect_b32 s26, -2, 3
	s_add_i32 s26, s26, s75
	s_lshl_b32 s26, s26, 15
	s_add_i32 s26, s26, s44
	s_add_u32 m0, s26, 0x2000
	v_lshl_add_u64 v[150:151], v[162:163], 0, s[28:29]
	global_load_lds_dwordx4 v[150:151], off
	s_add_u32 m0, s30, 0x2000
	v_lshl_add_u64 v[150:151], v[150:151], 0, 64
	global_load_lds_dwordx4 v[150:151], off
	s_add_u32 s28, s28, 64
	s_addc_u32 s29, s29, 0
.Lg3_O_sb1:
	s_waitcnt lgkmcnt(0)
	v_mfma_f32_16x16x32_bf16 v[94:97], v[130:133], v[202:205], v[94:97]
	ds_read_b128 v[146:149], v64 offset:4096
	ds_read_b128 v[150:153], v64 offset:5120
	v_mfma_f32_16x16x32_bf16 v[90:93], v[134:137], v[202:205], v[90:93]
	v_mfma_f32_16x16x32_bf16 v[86:89], v[138:141], v[202:205], v[86:89]
	v_mfma_f32_16x16x32_bf16 v[82:85], v[142:145], v[202:205], v[82:85]
	v_mfma_f32_16x16x32_bf16 v[78:81], v[130:133], v[206:209], v[78:81]
	v_mfma_f32_16x16x32_bf16 v[74:77], v[134:137], v[206:209], v[74:77]
	v_mfma_f32_16x16x32_bf16 v[70:73], v[138:141], v[206:209], v[70:73]
	v_mfma_f32_16x16x32_bf16 v[66:69], v[142:145], v[206:209], v[66:69]
	s_cmp_lt_u32 s25, s45
	s_cbranch_scc0 .Lg3_O_sb
	s_sub_u32 s28, s28, 64
	s_subb_u32 s29, s29, 0
	s_cmp_gt_i32 s75, 0
	s_cselect_b32 s30, -1, 4
	s_add_i32 s30, s30, s75
	s_lshl_b32 s30, s30, 15
	s_add_i32 s30, s30, s44
	s_cmp_gt_i32 s75, 1
	s_cselect_b32 s26, -2, 3
	s_add_i32 s26, s26, s75
	s_lshl_b32 s26, s26, 15
	s_add_i32 s26, s26, s44
	s_add_u32 m0, s26, 0x4000
	v_lshl_add_u64 v[202:203], v[160:161], 0, s[28:29]
	global_load_lds_dwordx4 v[202:203], off
	s_add_u32 m0, s30, 0x4000
	v_lshl_add_u64 v[202:203], v[202:203], 0, 64
	global_load_lds_dwordx4 v[202:203], off
	s_add_u32 m0, s26, 0x6000
	v_lshl_add_u64 v[202:203], v[158:159], 0, s[28:29]
	global_load_lds_dwordx4 v[202:203], off
	s_add_u32 m0, s30, 0x6000
	v_lshl_add_u64 v[202:203], v[202:203], 0, 64
	global_load_lds_dwordx4 v[202:203], off
	s_add_u32 s28, s28, 64
	s_addc_u32 s29, s29, 0

.LBB0_1412:
	v_readfirstlane_b32 s40, v198
	v_readfirstlane_b32 s30, v166
	v_mov_b32_e32 v130, 0
	v_mov_b32_e32 v131, 0
	v_mov_b32_e32 v132, 0
	v_mov_b32_e32 v133, 0
	v_mov_b32_e32 v134, 0
	v_mov_b32_e32 v135, 0
	v_mov_b32_e32 v136, 0
	v_mov_b32_e32 v137, 0
	v_mov_b32_e32 v138, 0
	v_mov_b32_e32 v139, 0
	v_mov_b32_e32 v140, 0
	v_mov_b32_e32 v141, 0
	v_mov_b32_e32 v142, 0
	v_mov_b32_e32 v143, 0
	v_mov_b32_e32 v144, 0
	v_mov_b32_e32 v145, 0
	v_mov_b32_e32 v202, 0
	v_mov_b32_e32 v203, 0
	v_mov_b32_e32 v204, 0
	v_mov_b32_e32 v205, 0
	v_mov_b32_e32 v206, 0
	v_mov_b32_e32 v207, 0
	v_mov_b32_e32 v208, 0
	v_mov_b32_e32 v209, 0
	s_lshr_b32 s30, s30, 8
	s_cmp_eq_u32 s30, 0
	s_mov_b32 s41, 28
	s_mov_b32 s27, 0
	s_lshl_b32 s26, s1, 15
	v_or_b32_e32 v254, s26, v200
	v_add_u32_e32 v254, v254, v197
	v_add_u32_e32 v64, s26, v199
	v_add_u32_e32 v64, v64, v197
	s_waitcnt vmcnt(12)

.Lg4_Ew:
.Lg4_O:
	s_waitcnt lgkmcnt(0)
	s_barrier
	ds_read_b128 v[130:133], v254 offset:16384
	ds_read_b128 v[134:137], v254 offset:17408
	ds_read_b128 v[150:153], v64
	ds_read_b128 v[146:149], v64 offset:1024
	v_mfma_f32_16x16x32_bf16 v[24:27], v[246:249], v[202:205], v[24:27]
	v_mfma_f32_16x16x32_bf16 v[20:23], v[250:253], v[202:205], v[20:23]
	v_mfma_f32_16x16x32_bf16 v[16:19], v[138:141], v[202:205], v[16:19]
	v_mfma_f32_16x16x32_bf16 v[12:15], v[142:145], v[202:205], v[12:15]
	v_mfma_f32_16x16x32_bf16 v[8:11], v[246:249], v[206:209], v[8:11]
	v_mfma_f32_16x16x32_bf16 v[4:7], v[250:253], v[206:209], v[4:7]
	v_mfma_f32_16x16x32_bf16 v[0:3], v[138:141], v[206:209], v[0:3]
	v_mfma_f32_16x16x32_bf16 v[28:31], v[142:145], v[206:209], v[28:31]
	ds_read_b128 v[138:141], v254 offset:18432
	ds_read_b128 v[142:145], v254 offset:19456
	s_cmp_lt_u32 s75, s41
	s_cbranch_scc0 .Lg4_O_sa
	s_sub_u32 s28, s28, 64
	s_subb_u32 s29, s29, 0
	s_cmp_gt_i32 s1, 0
	s_cselect_b32 s30, -1, 4
	s_add_i32 s30, s30, s1
	s_lshl_b32 s30, s30, 15
	s_add_i32 s30, s30, s40
	s_cmp_gt_i32 s1, 1
	s_cselect_b32 s26, -2, 3
	s_add_i32 s26, s26, s1
	s_lshl_b32 s26, s26, 15
	s_add_i32 s26, s26, s40
	s_mov_b32 m0, s26
	v_lshl_add_u64 v[202:203], v[164:165], 0, s[28:29]
	global_load_lds_dwordx4 v[202:203], off
	s_mov_b32 m0, s30
	v_lshl_add_u64 v[202:203], v[202:203], 0, 64
	global_load_lds_dwordx4 v[202:203], off
	s_add_u32 s28, s28, 64
	s_addc_u32 s29, s29, 0
.Lg4_O_sa:
	ds_read_b128 v[202:205], v64 offset:2048
	ds_read_b128 v[206:209], v64 offset:3072
	s_waitcnt lgkmcnt(4)
	v_mfma_f32_16x16x32_bf16 v[126:129], v[130:133], v[150:153], v[126:129]
	v_mfma_f32_16x16x32_bf16 v[122:125], v[134:137], v[150:153], v[122:125]
	v_mfma_f32_16x16x32_bf16 v[110:113], v[130:133], v[146:149], v[110:113]
	v_mfma_f32_16x16x32_bf16 v[106:109], v[134:137], v[146:149], v[106:109]
	s_waitcnt lgkmcnt(2)
	v_mfma_f32_16x16x32_bf16 v[118:121], v[138:141], v[150:153], v[118:121]
	v_mfma_f32_16x16x32_bf16 v[114:117], v[142:145], v[150:153], v[114:117]
	v_mfma_f32_16x16x32_bf16 v[102:105], v[138:141], v[146:149], v[102:105]
	v_mfma_f32_16x16x32_bf16 v[98:101], v[142:145], v[146:149], v[98:101]
	s_cmp_lt_u32 s75, s41
	s_cbranch_scc0 .Lg4_O_sb1
	s_sub_u32 s28, s28, 64
	s_subb_u32 s29, s29, 0
	s_cmp_gt_i32 s1, 0
	s_cselect_b32 s30, -1, 4
	s_add_i32 s30, s30, s1
	s_lshl_b32 s30, s30, 15
	s_add_i32 s30, s30, s40
	s_cmp_gt_i32 s1, 1
	s_cselect_b32 s26, -2, 3
	s_add_i32 s26, s26, s1
	s_lshl_b32 s26, s26, 15
	s_add_i32 s26, s26, s40
	s_add_u32 m0, s26, 0x2000
	v_lshl_add_u64 v[150:151], v[162:163], 0, s[28:29]
	global_load_lds_dwordx4 v[150:151], off
	s_add_u32 m0, s30, 0x2000
	v_lshl_add_u64 v[150:151], v[150:151], 0, 64
	global_load_lds_dwordx4 v[150:151], off
	s_add_u32 s28, s28, 64
	s_addc_u32 s29, s29, 0
.Lg4_O_sb1:
	s_waitcnt lgkmcnt(0)
	v_mfma_f32_16x16x32_bf16 v[94:97], v[130:133], v[202:205], v[94:97]
	ds_read_b128 v[146:149], v64 offset:4096
	ds_read_b128 v[150:153], v64 offset:5120
	v_mfma_f32_16x16x32_bf16 v[90:93], v[134:137], v[202:205], v[90:93]
	v_mfma_f32_16x16x32_bf16 v[86:89], v[138:141], v[202:205], v[86:89]
	v_mfma_f32_16x16x32_bf16 v[82:85], v[142:145], v[202:205], v[82:85]
	v_mfma_f32_16x16x32_bf16 v[78:81], v[130:133], v[206:209], v[78:81]
	v_mfma_f32_16x16x32_bf16 v[74:77], v[134:137], v[206:209], v[74:77]
	v_mfma_f32_16x16x32_bf16 v[70:73], v[138:141], v[206:209], v[70:73]
	v_mfma_f32_16x16x32_bf16 v[66:69], v[142:145], v[206:209], v[66:69]
	s_cmp_lt_u32 s75, s41
	s_cbranch_scc0 .Lg4_O_sb
	s_sub_u32 s28, s28, 64
	s_subb_u32 s29, s29, 0
	s_cmp_gt_i32 s1, 0
	s_cselect_b32 s30, -1, 4
	s_add_i32 s30, s30, s1
	s_lshl_b32 s30, s30, 15
	s_add_i32 s30, s30, s40
	s_cmp_gt_i32 s1, 1
	s_cselect_b32 s26, -2, 3
	s_add_i32 s26, s26, s1
	s_lshl_b32 s26, s26, 15
	s_add_i32 s26, s26, s40
	s_add_u32 m0, s26, 0x4000
	v_lshl_add_u64 v[202:203], v[160:161], 0, s[28:29]
	global_load_lds_dwordx4 v[202:203], off
	s_add_u32 m0, s30, 0x4000
	v_lshl_add_u64 v[202:203], v[202:203], 0, 64
	global_load_lds_dwordx4 v[202:203], off
	s_add_u32 m0, s26, 0x6000
	v_lshl_add_u64 v[202:203], v[158:159], 0, s[28:29]
	global_load_lds_dwordx4 v[202:203], off
	s_add_u32 m0, s30, 0x6000
	v_lshl_add_u64 v[202:203], v[202:203], 0, 64
	global_load_lds_dwordx4 v[202:203], off
	s_add_u32 s28, s28, 64
	s_addc_u32 s29, s29, 0

.LBB0_1497:
	v_readfirstlane_b32 s28, v200
	v_readfirstlane_b32 s26, v166
	v_mov_b32_e32 v130, 0
	v_mov_b32_e32 v131, 0
	v_mov_b32_e32 v132, 0
	v_mov_b32_e32 v133, 0
	v_mov_b32_e32 v134, 0
	v_mov_b32_e32 v135, 0
	v_mov_b32_e32 v136, 0
	v_mov_b32_e32 v137, 0
	v_mov_b32_e32 v138, 0
	v_mov_b32_e32 v139, 0
	v_mov_b32_e32 v140, 0
	v_mov_b32_e32 v141, 0
	v_mov_b32_e32 v142, 0
	v_mov_b32_e32 v143, 0
	v_mov_b32_e32 v144, 0
	v_mov_b32_e32 v145, 0
	v_mov_b32_e32 v202, 0
	v_mov_b32_e32 v203, 0
	v_mov_b32_e32 v204, 0
	v_mov_b32_e32 v205, 0
	v_mov_b32_e32 v206, 0
	v_mov_b32_e32 v207, 0
	v_mov_b32_e32 v208, 0
	v_mov_b32_e32 v209, 0
	s_lshr_b32 s26, s26, 8
	s_cmp_eq_u32 s26, 0
	s_mov_b32 s29, 28
	s_mov_b32 s25, 0
	s_lshl_b32 s24, s65, 15
	v_or_b32_e32 v254, s24, v199
	v_add_u32_e32 v254, v254, v197
	v_add_u32_e32 v64, s24, v198
	v_add_u32_e32 v64, v64, v197
	s_waitcnt vmcnt(12)

.Lg5_Ew:
.Lg5_O:
	s_waitcnt lgkmcnt(0)
	s_barrier
	ds_read_b128 v[130:133], v254 offset:16384
	ds_read_b128 v[134:137], v254 offset:17408
	ds_read_b128 v[150:153], v64
	ds_read_b128 v[146:149], v64 offset:1024
	v_mfma_f32_16x16x32_bf16 v[28:31], v[246:249], v[202:205], v[28:31]
	v_mfma_f32_16x16x32_bf16 v[24:27], v[250:253], v[202:205], v[24:27]
	v_mfma_f32_16x16x32_bf16 v[20:23], v[138:141], v[202:205], v[20:23]
	v_mfma_f32_16x16x32_bf16 v[16:19], v[142:145], v[202:205], v[16:19]
	v_mfma_f32_16x16x32_bf16 v[12:15], v[246:249], v[206:209], v[12:15]
	v_mfma_f32_16x16x32_bf16 v[8:11], v[250:253], v[206:209], v[8:11]
	v_mfma_f32_16x16x32_bf16 v[4:7], v[138:141], v[206:209], v[4:7]
	v_mfma_f32_16x16x32_bf16 v[0:3], v[142:145], v[206:209], v[0:3]
	ds_read_b128 v[138:141], v254 offset:18432
	ds_read_b128 v[142:145], v254 offset:19456
	s_cmp_lt_u32 s41, s29
	s_cbranch_scc0 .Lg5_O_sa
	s_sub_u32 s0, s0, 64
	s_subb_u32 s1, s1, 0
	s_cmp_gt_i32 s65, 0
	s_cselect_b32 s26, -1, 4
	s_add_i32 s26, s26, s65
	s_lshl_b32 s26, s26, 15
	s_add_i32 s26, s26, s28
	s_cmp_gt_i32 s65, 1
	s_cselect_b32 s24, -2, 3
	s_add_i32 s24, s24, s65
	s_lshl_b32 s24, s24, 15
	s_add_i32 s24, s24, s28
	s_mov_b32 m0, s24
	v_lshl_add_u64 v[202:203], v[164:165], 0, s[0:1]
	global_load_lds_dwordx4 v[202:203], off
	s_mov_b32 m0, s26
	v_lshl_add_u64 v[202:203], v[202:203], 0, 64
	global_load_lds_dwordx4 v[202:203], off
	s_add_u32 s0, s0, 64
	s_addc_u32 s1, s1, 0
.Lg5_O_sa:
	ds_read_b128 v[202:205], v64 offset:2048
	ds_read_b128 v[206:209], v64 offset:3072
	s_waitcnt lgkmcnt(4)
	v_mfma_f32_16x16x32_bf16 v[126:129], v[130:133], v[150:153], v[126:129]
	v_mfma_f32_16x16x32_bf16 v[122:125], v[134:137], v[150:153], v[122:125]
	v_mfma_f32_16x16x32_bf16 v[110:113], v[130:133], v[146:149], v[110:113]
	v_mfma_f32_16x16x32_bf16 v[106:109], v[134:137], v[146:149], v[106:109]
	s_waitcnt lgkmcnt(2)
	v_mfma_f32_16x16x32_bf16 v[118:121], v[138:141], v[150:153], v[118:121]
	v_mfma_f32_16x16x32_bf16 v[114:117], v[142:145], v[150:153], v[114:117]
	v_mfma_f32_16x16x32_bf16 v[102:105], v[138:141], v[146:149], v[102:105]
	v_mfma_f32_16x16x32_bf16 v[98:101], v[142:145], v[146:149], v[98:101]
	s_cmp_lt_u32 s41, s29
	s_cbranch_scc0 .Lg5_O_sb1
	s_sub_u32 s0, s0, 64
	s_subb_u32 s1, s1, 0
	s_cmp_gt_i32 s65, 0
	s_cselect_b32 s26, -1, 4
	s_add_i32 s26, s26, s65
	s_lshl_b32 s26, s26, 15
	s_add_i32 s26, s26, s28
	s_cmp_gt_i32 s65, 1
	s_cselect_b32 s24, -2, 3
	s_add_i32 s24, s24, s65
	s_lshl_b32 s24, s24, 15
	s_add_i32 s24, s24, s28
	s_add_u32 m0, s24, 0x2000
	v_lshl_add_u64 v[150:151], v[162:163], 0, s[0:1]
	global_load_lds_dwordx4 v[150:151], off
	s_add_u32 m0, s26, 0x2000
	v_lshl_add_u64 v[150:151], v[150:151], 0, 64
	global_load_lds_dwordx4 v[150:151], off
	s_add_u32 s0, s0, 64
	s_addc_u32 s1, s1, 0
.Lg5_O_sb1:
	s_waitcnt lgkmcnt(0)
	v_mfma_f32_16x16x32_bf16 v[94:97], v[130:133], v[202:205], v[94:97]
	ds_read_b128 v[146:149], v64 offset:4096
	ds_read_b128 v[150:153], v64 offset:5120
	v_mfma_f32_16x16x32_bf16 v[90:93], v[134:137], v[202:205], v[90:93]
	v_mfma_f32_16x16x32_bf16 v[86:89], v[138:141], v[202:205], v[86:89]
	v_mfma_f32_16x16x32_bf16 v[82:85], v[142:145], v[202:205], v[82:85]
	v_mfma_f32_16x16x32_bf16 v[78:81], v[130:133], v[206:209], v[78:81]
	v_mfma_f32_16x16x32_bf16 v[74:77], v[134:137], v[206:209], v[74:77]
	v_mfma_f32_16x16x32_bf16 v[70:73], v[138:141], v[206:209], v[70:73]
	v_mfma_f32_16x16x32_bf16 v[66:69], v[142:145], v[206:209], v[66:69]
	s_cmp_lt_u32 s41, s29
	s_cbranch_scc0 .Lg5_O_sb
	s_sub_u32 s0, s0, 64
	s_subb_u32 s1, s1, 0
	s_cmp_gt_i32 s65, 0
	s_cselect_b32 s26, -1, 4
	s_add_i32 s26, s26, s65
	s_lshl_b32 s26, s26, 15
	s_add_i32 s26, s26, s28
	s_cmp_gt_i32 s65, 1
	s_cselect_b32 s24, -2, 3
	s_add_i32 s24, s24, s65
	s_lshl_b32 s24, s24, 15
	s_add_i32 s24, s24, s28
	s_add_u32 m0, s24, 0x4000
	v_lshl_add_u64 v[202:203], v[160:161], 0, s[0:1]
	global_load_lds_dwordx4 v[202:203], off
	s_add_u32 m0, s26, 0x4000
	v_lshl_add_u64 v[202:203], v[202:203], 0, 64
	global_load_lds_dwordx4 v[202:203], off
	s_add_u32 m0, s24, 0x6000
	v_lshl_add_u64 v[202:203], v[158:159], 0, s[0:1]
	global_load_lds_dwordx4 v[202:203], off
	s_add_u32 m0, s26, 0x6000
	v_lshl_add_u64 v[202:203], v[202:203], 0, 64
	global_load_lds_dwordx4 v[202:203], off
	s_add_u32 s0, s0, 64
	s_addc_u32 s1, s1, 0

.LBB0_1639:
	v_readfirstlane_b32 s40, v200
	v_readfirstlane_b32 s27, v166
	v_mov_b32_e32 v130, 0
	v_mov_b32_e32 v131, 0
	v_mov_b32_e32 v132, 0
	v_mov_b32_e32 v133, 0
	v_mov_b32_e32 v134, 0
	v_mov_b32_e32 v135, 0
	v_mov_b32_e32 v136, 0
	v_mov_b32_e32 v137, 0
	v_mov_b32_e32 v138, 0
	v_mov_b32_e32 v139, 0
	v_mov_b32_e32 v140, 0
	v_mov_b32_e32 v141, 0
	v_mov_b32_e32 v142, 0
	v_mov_b32_e32 v143, 0
	v_mov_b32_e32 v144, 0
	v_mov_b32_e32 v145, 0
	v_mov_b32_e32 v202, 0
	v_mov_b32_e32 v203, 0
	v_mov_b32_e32 v204, 0
	v_mov_b32_e32 v205, 0
	v_mov_b32_e32 v206, 0
	v_mov_b32_e32 v207, 0
	v_mov_b32_e32 v208, 0
	v_mov_b32_e32 v209, 0
	s_lshr_b32 s27, s27, 8
	s_cmp_eq_u32 s27, 0
	s_mov_b32 s41, 28
	s_mov_b32 s26, 0
	s_lshl_b32 s25, s65, 15
	v_or_b32_e32 v254, s25, v199
	v_add_u32_e32 v254, v254, v197
	v_add_u32_e32 v64, s25, v198
	v_add_u32_e32 v64, v64, v197
	s_waitcnt vmcnt(12)

.Lg6_Ew:
.Lg6_O:
	s_waitcnt lgkmcnt(0)
	s_barrier
	ds_read_b128 v[130:133], v254 offset:16384
	ds_read_b128 v[134:137], v254 offset:17408
	ds_read_b128 v[150:153], v64
	ds_read_b128 v[146:149], v64 offset:1024
	v_mfma_f32_16x16x32_bf16 v[28:31], v[246:249], v[202:205], v[28:31]
	v_mfma_f32_16x16x32_bf16 v[24:27], v[250:253], v[202:205], v[24:27]
	v_mfma_f32_16x16x32_bf16 v[20:23], v[138:141], v[202:205], v[20:23]
	v_mfma_f32_16x16x32_bf16 v[16:19], v[142:145], v[202:205], v[16:19]
	v_mfma_f32_16x16x32_bf16 v[12:15], v[246:249], v[206:209], v[12:15]
	v_mfma_f32_16x16x32_bf16 v[8:11], v[250:253], v[206:209], v[8:11]
	v_mfma_f32_16x16x32_bf16 v[4:7], v[138:141], v[206:209], v[4:7]
	v_mfma_f32_16x16x32_bf16 v[0:3], v[142:145], v[206:209], v[0:3]
	ds_read_b128 v[138:141], v254 offset:18432
	ds_read_b128 v[142:145], v254 offset:19456
	s_cmp_lt_u32 s1, s41
	s_cbranch_scc0 .Lg6_O_sa
	s_sub_u32 s28, s28, 64
	s_subb_u32 s29, s29, 0
	s_cmp_gt_i32 s65, 0
	s_cselect_b32 s27, -1, 4
	s_add_i32 s27, s27, s65
	s_lshl_b32 s27, s27, 15
	s_add_i32 s27, s27, s40
	s_cmp_gt_i32 s65, 1
	s_cselect_b32 s25, -2, 3
	s_add_i32 s25, s25, s65
	s_lshl_b32 s25, s25, 15
	s_add_i32 s25, s25, s40
	s_mov_b32 m0, s25
	v_lshl_add_u64 v[202:203], v[164:165], 0, s[28:29]
	global_load_lds_dwordx4 v[202:203], off
	s_mov_b32 m0, s27
	v_lshl_add_u64 v[202:203], v[202:203], 0, 64
	global_load_lds_dwordx4 v[202:203], off
	s_add_u32 s28, s28, 64
	s_addc_u32 s29, s29, 0
.Lg6_O_sa:
	ds_read_b128 v[202:205], v64 offset:2048
	ds_read_b128 v[206:209], v64 offset:3072
	s_waitcnt lgkmcnt(4)
	v_mfma_f32_16x16x32_bf16 v[126:129], v[130:133], v[150:153], v[126:129]
	v_mfma_f32_16x16x32_bf16 v[122:125], v[134:137], v[150:153], v[122:125]
	v_mfma_f32_16x16x32_bf16 v[110:113], v[130:133], v[146:149], v[110:113]
	v_mfma_f32_16x16x32_bf16 v[106:109], v[134:137], v[146:149], v[106:109]
	s_waitcnt lgkmcnt(2)
	v_mfma_f32_16x16x32_bf16 v[118:121], v[138:141], v[150:153], v[118:121]
	v_mfma_f32_16x16x32_bf16 v[114:117], v[142:145], v[150:153], v[114:117]
	v_mfma_f32_16x16x32_bf16 v[102:105], v[138:141], v[146:149], v[102:105]
	v_mfma_f32_16x16x32_bf16 v[98:101], v[142:145], v[146:149], v[98:101]
	s_cmp_lt_u32 s1, s41
	s_cbranch_scc0 .Lg6_O_sb1
	s_sub_u32 s28, s28, 64
	s_subb_u32 s29, s29, 0
	s_cmp_gt_i32 s65, 0
	s_cselect_b32 s27, -1, 4
	s_add_i32 s27, s27, s65
	s_lshl_b32 s27, s27, 15
	s_add_i32 s27, s27, s40
	s_cmp_gt_i32 s65, 1
	s_cselect_b32 s25, -2, 3
	s_add_i32 s25, s25, s65
	s_lshl_b32 s25, s25, 15
	s_add_i32 s25, s25, s40
	s_add_u32 m0, s25, 0x2000
	v_lshl_add_u64 v[150:151], v[162:163], 0, s[28:29]
	global_load_lds_dwordx4 v[150:151], off
	s_add_u32 m0, s27, 0x2000
	v_lshl_add_u64 v[150:151], v[150:151], 0, 64
	global_load_lds_dwordx4 v[150:151], off
	s_add_u32 s28, s28, 64
	s_addc_u32 s29, s29, 0
.Lg6_O_sb1:
	s_waitcnt lgkmcnt(0)
	v_mfma_f32_16x16x32_bf16 v[94:97], v[130:133], v[202:205], v[94:97]
	ds_read_b128 v[146:149], v64 offset:4096
	ds_read_b128 v[150:153], v64 offset:5120
	v_mfma_f32_16x16x32_bf16 v[90:93], v[134:137], v[202:205], v[90:93]
	v_mfma_f32_16x16x32_bf16 v[86:89], v[138:141], v[202:205], v[86:89]
	v_mfma_f32_16x16x32_bf16 v[82:85], v[142:145], v[202:205], v[82:85]
	v_mfma_f32_16x16x32_bf16 v[78:81], v[130:133], v[206:209], v[78:81]
	v_mfma_f32_16x16x32_bf16 v[74:77], v[134:137], v[206:209], v[74:77]
	v_mfma_f32_16x16x32_bf16 v[70:73], v[138:141], v[206:209], v[70:73]
	v_mfma_f32_16x16x32_bf16 v[66:69], v[142:145], v[206:209], v[66:69]
	s_cmp_lt_u32 s1, s41
	s_cbranch_scc0 .Lg6_O_sb
	s_sub_u32 s28, s28, 64
	s_subb_u32 s29, s29, 0
	s_cmp_gt_i32 s65, 0
	s_cselect_b32 s27, -1, 4
	s_add_i32 s27, s27, s65
	s_lshl_b32 s27, s27, 15
	s_add_i32 s27, s27, s40
	s_cmp_gt_i32 s65, 1
	s_cselect_b32 s25, -2, 3
	s_add_i32 s25, s25, s65
	s_lshl_b32 s25, s25, 15
	s_add_i32 s25, s25, s40
	s_add_u32 m0, s25, 0x4000
	v_lshl_add_u64 v[202:203], v[160:161], 0, s[28:29]
	global_load_lds_dwordx4 v[202:203], off
	s_add_u32 m0, s27, 0x4000
	v_lshl_add_u64 v[202:203], v[202:203], 0, 64
	global_load_lds_dwordx4 v[202:203], off
	s_add_u32 m0, s25, 0x6000
	v_lshl_add_u64 v[202:203], v[158:159], 0, s[28:29]
	global_load_lds_dwordx4 v[202:203], off
	s_add_u32 m0, s27, 0x6000
	v_lshl_add_u64 v[202:203], v[202:203], 0, 64
	global_load_lds_dwordx4 v[202:203], off
	s_add_u32 s28, s28, 64
	s_addc_u32 s29, s29, 0

.LBB0_1785:
	v_readfirstlane_b32 s30, v200
	v_readfirstlane_b32 s28, v166
	v_mov_b32_e32 v130, 0
	v_mov_b32_e32 v131, 0
	v_mov_b32_e32 v132, 0
	v_mov_b32_e32 v133, 0
	v_mov_b32_e32 v134, 0
	v_mov_b32_e32 v135, 0
	v_mov_b32_e32 v136, 0
	v_mov_b32_e32 v137, 0
	v_mov_b32_e32 v138, 0
	v_mov_b32_e32 v139, 0
	v_mov_b32_e32 v140, 0
	v_mov_b32_e32 v141, 0
	v_mov_b32_e32 v142, 0
	v_mov_b32_e32 v143, 0
	v_mov_b32_e32 v144, 0
	v_mov_b32_e32 v145, 0
	v_mov_b32_e32 v202, 0
	v_mov_b32_e32 v203, 0
	v_mov_b32_e32 v204, 0
	v_mov_b32_e32 v205, 0
	v_mov_b32_e32 v206, 0
	v_mov_b32_e32 v207, 0
	v_mov_b32_e32 v208, 0
	v_mov_b32_e32 v209, 0
	s_lshr_b32 s28, s28, 8
	s_cmp_eq_u32 s28, 0
	s_mov_b32 s31, 84
	s_mov_b32 s27, 0
	s_lshl_b32 s26, s41, 15
	v_or_b32_e32 v254, s26, v199
	v_add_u32_e32 v254, v254, v197
	v_add_u32_e32 v64, s26, v198
	v_add_u32_e32 v64, v64, v197
	s_waitcnt vmcnt(12)

.Lg7_Ew:
.Lg7_O:
	s_waitcnt lgkmcnt(0)
	s_barrier
	ds_read_b128 v[130:133], v254 offset:16384
	ds_read_b128 v[134:137], v254 offset:17408
	ds_read_b128 v[150:153], v64
	ds_read_b128 v[146:149], v64 offset:1024
	v_mfma_f32_16x16x32_bf16 v[28:31], v[246:249], v[202:205], v[28:31]
	v_mfma_f32_16x16x32_bf16 v[24:27], v[250:253], v[202:205], v[24:27]
	v_mfma_f32_16x16x32_bf16 v[20:23], v[138:141], v[202:205], v[20:23]
	v_mfma_f32_16x16x32_bf16 v[16:19], v[142:145], v[202:205], v[16:19]
	v_mfma_f32_16x16x32_bf16 v[12:15], v[246:249], v[206:209], v[12:15]
	v_mfma_f32_16x16x32_bf16 v[8:11], v[250:253], v[206:209], v[8:11]
	v_mfma_f32_16x16x32_bf16 v[4:7], v[138:141], v[206:209], v[4:7]
	v_mfma_f32_16x16x32_bf16 v[0:3], v[142:145], v[206:209], v[0:3]
	ds_read_b128 v[138:141], v254 offset:18432
	ds_read_b128 v[142:145], v254 offset:19456
	s_cmp_lt_u32 s45, s31
	s_cbranch_scc0 .Lg7_O_sa
	s_sub_u32 s0, s0, 64
	s_subb_u32 s1, s1, 0
	s_cmp_gt_i32 s41, 0
	s_cselect_b32 s28, -1, 4
	s_add_i32 s28, s28, s41
	s_lshl_b32 s28, s28, 15
	s_add_i32 s28, s28, s30
	s_cmp_gt_i32 s41, 1
	s_cselect_b32 s26, -2, 3
	s_add_i32 s26, s26, s41
	s_lshl_b32 s26, s26, 15
	s_add_i32 s26, s26, s30
	s_mov_b32 m0, s26
	v_lshl_add_u64 v[202:203], v[164:165], 0, s[0:1]
	global_load_lds_dwordx4 v[202:203], off
	s_mov_b32 m0, s28
	v_lshl_add_u64 v[202:203], v[202:203], 0, 64
	global_load_lds_dwordx4 v[202:203], off
	s_add_u32 s0, s0, 64
	s_addc_u32 s1, s1, 0
.Lg7_O_sa:
	ds_read_b128 v[202:205], v64 offset:2048
	ds_read_b128 v[206:209], v64 offset:3072
	s_waitcnt lgkmcnt(4)
	v_mfma_f32_16x16x32_bf16 v[126:129], v[130:133], v[150:153], v[126:129]
	v_mfma_f32_16x16x32_bf16 v[122:125], v[134:137], v[150:153], v[122:125]
	v_mfma_f32_16x16x32_bf16 v[110:113], v[130:133], v[146:149], v[110:113]
	v_mfma_f32_16x16x32_bf16 v[106:109], v[134:137], v[146:149], v[106:109]
	s_waitcnt lgkmcnt(2)
	v_mfma_f32_16x16x32_bf16 v[118:121], v[138:141], v[150:153], v[118:121]
	v_mfma_f32_16x16x32_bf16 v[114:117], v[142:145], v[150:153], v[114:117]
	v_mfma_f32_16x16x32_bf16 v[102:105], v[138:141], v[146:149], v[102:105]
	v_mfma_f32_16x16x32_bf16 v[98:101], v[142:145], v[146:149], v[98:101]
	s_cmp_lt_u32 s45, s31
	s_cbranch_scc0 .Lg7_O_sb1
	s_sub_u32 s0, s0, 64
	s_subb_u32 s1, s1, 0
	s_cmp_gt_i32 s41, 0
	s_cselect_b32 s28, -1, 4
	s_add_i32 s28, s28, s41
	s_lshl_b32 s28, s28, 15
	s_add_i32 s28, s28, s30
	s_cmp_gt_i32 s41, 1
	s_cselect_b32 s26, -2, 3
	s_add_i32 s26, s26, s41
	s_lshl_b32 s26, s26, 15
	s_add_i32 s26, s26, s30
	s_add_u32 m0, s26, 0x2000
	v_lshl_add_u64 v[150:151], v[162:163], 0, s[0:1]
	global_load_lds_dwordx4 v[150:151], off
	s_add_u32 m0, s28, 0x2000
	v_lshl_add_u64 v[150:151], v[150:151], 0, 64
	global_load_lds_dwordx4 v[150:151], off
	s_add_u32 s0, s0, 64
	s_addc_u32 s1, s1, 0
.Lg7_O_sb1:
	s_waitcnt lgkmcnt(0)
	v_mfma_f32_16x16x32_bf16 v[94:97], v[130:133], v[202:205], v[94:97]
	ds_read_b128 v[146:149], v64 offset:4096
	ds_read_b128 v[150:153], v64 offset:5120
	v_mfma_f32_16x16x32_bf16 v[90:93], v[134:137], v[202:205], v[90:93]
	v_mfma_f32_16x16x32_bf16 v[86:89], v[138:141], v[202:205], v[86:89]
	v_mfma_f32_16x16x32_bf16 v[82:85], v[142:145], v[202:205], v[82:85]
	v_mfma_f32_16x16x32_bf16 v[78:81], v[130:133], v[206:209], v[78:81]
	v_mfma_f32_16x16x32_bf16 v[74:77], v[134:137], v[206:209], v[74:77]
	v_mfma_f32_16x16x32_bf16 v[70:73], v[138:141], v[206:209], v[70:73]
	v_mfma_f32_16x16x32_bf16 v[66:69], v[142:145], v[206:209], v[66:69]
	s_cmp_lt_u32 s45, s31
	s_cbranch_scc0 .Lg7_O_sb
	s_sub_u32 s0, s0, 64
	s_subb_u32 s1, s1, 0
	s_cmp_gt_i32 s41, 0
	s_cselect_b32 s28, -1, 4
	s_add_i32 s28, s28, s41
	s_lshl_b32 s28, s28, 15
	s_add_i32 s28, s28, s30
	s_cmp_gt_i32 s41, 1
	s_cselect_b32 s26, -2, 3
	s_add_i32 s26, s26, s41
	s_lshl_b32 s26, s26, 15
	s_add_i32 s26, s26, s30
	s_add_u32 m0, s26, 0x4000
	v_lshl_add_u64 v[202:203], v[160:161], 0, s[0:1]
	global_load_lds_dwordx4 v[202:203], off
	s_add_u32 m0, s28, 0x4000
	v_lshl_add_u64 v[202:203], v[202:203], 0, 64
	global_load_lds_dwordx4 v[202:203], off
	s_add_u32 m0, s26, 0x6000
	v_lshl_add_u64 v[202:203], v[158:159], 0, s[0:1]
	global_load_lds_dwordx4 v[202:203], off
	s_add_u32 m0, s28, 0x6000
	v_lshl_add_u64 v[202:203], v[202:203], 0, 64
	global_load_lds_dwordx4 v[202:203], off
	s_add_u32 s0, s0, 64
	s_addc_u32 s1, s1, 0
